# weight conversion windows rebalanced: G1 l0 tail 7 tiles per idle workgroup, last 192 W_up tiles converted by the HGRN workgroups at the end of layer 0's recurrence phase
# baseline (speedup 1.0000x reference)
; #define LAS __attribute__((address_space(3)))
; __device__ __forceinline__ int bidx() { int t = blockIdx.x; asm volatile("" : "+s"(t)); return t; }
; __device__ __forceinline__ void convert_tiles(int t0, int t1, int step, LAS float* tile) {
;     int t = t0;
;     if (t < t1) {
;         TileJob cur = tile_job(t); f32x4 v[2]; tile_load(cur, v);
; __device__ __forceinline__ void phase_rec(const Params& p, int l, LAS unsigned char* lds) {
;     for (int u = bidx(); u < 256; u += gridDim.x) {
;         const int vhalf = u & 1, head = (u >> 1) & 3, mixer = (u >> 3) & 3, sg = u >> 5;
;         const int bi = sg * 8 + (u & 7);
;         if (mixer == 0) { rec_unit<0, true, false>(p, l, lds, sg, head, vhalf * 32);
;             if (l == 0) { convert_tiles(N_TILES_WIN0 + bi * 40, N_TILES_WIN0 + bi * 40 + 40, 1, (LAS float*)lds); copy_x_rows(bi * 132, 132); } }
;         else if (mixer == 1) rec_unit<1, true, false>(p, l, lds, sg, head, vhalf * 32);
;         else if (mixer == 2) { rec_unit_chunked<2>(p, l, lds, sg, head, vhalf); rec_unit<2, false, true>(p, l, lds, sg, head, vhalf * 32); rec_unit<3, false, true>(p, l, lds, sg, head, vhalf * 32);
;             if (l == 0) { convert_tiles(N_TILES_WIN0 + 2560 + bi * 35, N_TILES_WIN0 + 2560 + bi * 35 + 35, 1, (LAS float*)lds); copy_x_rows((64 + bi) * 132, 132); } }
;         else { rec_unit_chunked<3>(p, l, lds, sg, head, vhalf); rec_unit<1, false, true>(p, l, lds, sg, head, vhalf * 32); rec_unit<0, false, true>(p, l, lds, sg, head, vhalf * 32);
;             if (l == 0) convert_tiles(N_TILES_WIN0 + 4800 + bi * 14, N_TILES_WIN0 + 4800 + bi * 14 + 14, 1, (LAS float*)lds); }
.LBB0_996:
	v_readlane_b32 s52, v252, 34
	v_readlane_b32 s54, v252, 36
	v_readlane_b32 s56, v252, 38
	v_readlane_b32 s58, v252, 40
	v_readlane_b32 s70, v252, 42
	v_readlane_b32 s74, v252, 44
	v_readlane_b32 s34, v252, 31
	s_mov_b64 s[4:5], 0
	v_readlane_b32 s53, v252, 35
	v_readlane_b32 s55, v252, 37
	v_readlane_b32 s57, v252, 39
	v_readlane_b32 s59, v252, 41
	v_readlane_b32 s71, v252, 43
	v_readlane_b32 s75, v252, 45
	v_readlane_b32 s35, v252, 32
	s_cmpk_lg_u32 s82, 0x100
	s_cbranch_scc1 .Lcvt_none
	s_cmp_eq_u32 s27, 1
	s_cbranch_scc1 .Lcvt_w1
	s_cmp_eq_u32 s27, 3
	s_cbranch_scc1 .Lcvt_w3
	s_cmp_eq_u32 s27, 7
	s_cbranch_scc1 .Lcvt_w7
	s_cmp_eq_u32 s27, 10
	s_cbranch_scc1 .Lcvt_w10
	s_cmp_eq_u32 s27, 16
	s_cbranch_scc0 .Lcvt_none
	s_sub_u32 s40, s17, 32
	s_cbranch_scc1 .Lcvt_none
	s_mul_i32 s40, s40, 5
	s_add_u32 s40, s40, 0x1680
	s_add_u32 s41, s40, 5
	s_min_u32 s41, s41, 0x1a80
	s_branch .Lcvt_go
.Lcvt_w1:
	s_sub_u32 s40, s17, 0x62
	s_cbranch_scc1 .Lcvt_none
	s_mul_i32 s40, s40, 7
	s_add_u32 s40, s40, 0x440
	s_add_u32 s41, s40, 7
	s_min_u32 s41, s41, 0x880
	s_branch .Lcvt_go
.Lcvt_w3:
	s_bfe_u32 s40, s17, 0x20003
	s_cmp_lg_u32 s40, 0
	s_cbranch_scc1 .Lcvt_none
	s_lshr_b32 s40, s17, 5
	s_lshl_b32 s40, s40, 3
	s_and_b32 s41, s17, 7
	s_add_u32 s40, s40, s41
	s_mul_i32 s40, s40, 3
	s_add_u32 s40, s40, 0x880
	s_add_u32 s41, s40, 3
	s_branch .Lcvt_go
